# barrier: leader issues L2 writeback before its L1 invalidate (invalidate moved off the leader critical path), pollers invalidate at poll entry
# speedup vs baseline: 1.0083x; 1.0045x over previous
.LBB0_241:
	v_readlane_b32 s2, v254, 8
	v_readlane_b32 s6, v254, 6
	v_readlane_b32 s7, v254, 7
	v_readlane_b32 s4, v254, 4
	v_readlane_b32 s5, v254, 5
	s_lshl_b32 s2, s2, 8
	s_add_u32 s2, s6, s2
	s_addc_u32 s3, s7, 0
	s_add_u32 s8, s2, 0x2400
	s_addc_u32 s9, s3, 0
	s_add_u32 s2, s2, 0x1400
	s_addc_u32 s3, s3, 0
	s_add_u32 s14, s4, 0x4200
	s_addc_u32 s15, s5, 0
	s_add_u32 s16, s4, 0x7400
	s_addc_u32 s17, s5, 0
	s_add_u32 s18, s6, 0x2400
	s_addc_u32 s19, s7, 0
	v_mov_b32_e32 v4, 1
	v_mov_b32_e32 v5, 0
	global_atomic_add v3, v5, v4, s[2:3] sc0
	s_waitcnt vmcnt(0) lgkmcnt(0)
	v_readfirstlane_b32 s10, v2
	v_readfirstlane_b32 s11, v0
	v_readfirstlane_b32 s12, v3
	s_add_i32 s12, s12, 1
	s_cmp_lg_u32 s12, s10
	s_cbranch_scc1 .Lxb1_poll
	buffer_wbl2 sc1
	s_waitcnt vmcnt(0)
	global_atomic_add v3, v5, v4, s[16:17] sc0
	s_waitcnt vmcnt(0)
	v_readfirstlane_b32 s12, v3
	s_add_i32 s12, s12, 1
	s_cmp_lg_u32 s12, s11
	s_cbranch_scc1 .Lxb1_poll
	global_atomic_add v5, v4, s[18:19]
	global_atomic_add v5, v4, s[18:19] offset:256
	global_atomic_add v5, v4, s[18:19] offset:512
	global_atomic_add v5, v4, s[18:19] offset:768
	global_atomic_add v5, v4, s[18:19] offset:1024
	global_atomic_add v5, v4, s[18:19] offset:1280
	global_atomic_add v5, v4, s[18:19] offset:1536
	global_atomic_add v5, v4, s[18:19] offset:1792
	global_atomic_add v5, v4, s[18:19] offset:2048
	global_atomic_add v5, v4, s[18:19] offset:2304
	global_atomic_add v5, v4, s[18:19] offset:2560
	global_atomic_add v5, v4, s[18:19] offset:2816
	global_atomic_add v5, v4, s[18:19] offset:3072
	global_atomic_add v5, v4, s[18:19] offset:3328
	global_atomic_add v5, v4, s[18:19] offset:3584
	global_atomic_add v5, v4, s[18:19] offset:3840
	buffer_inv sc1
	s_waitcnt vmcnt(0)
	s_branch .Lxb1_out
.Lxb1_poll:
	buffer_inv sc1
	s_mov_b32 s22, 0

.LBB0_692:
	v_readlane_b32 s2, v254, 8
	v_readlane_b32 s6, v254, 6
	v_readlane_b32 s7, v254, 7
	v_readlane_b32 s4, v254, 4
	v_readlane_b32 s5, v254, 5
	s_lshl_b32 s2, s2, 8
	s_add_u32 s2, s6, s2
	s_addc_u32 s3, s7, 0
	s_add_u32 s8, s2, 0x2400
	s_addc_u32 s9, s3, 0
	s_add_u32 s2, s2, 0x1400
	s_addc_u32 s3, s3, 0
	s_add_u32 s14, s4, 0x4200
	s_addc_u32 s15, s5, 0
	s_add_u32 s16, s4, 0x7400
	s_addc_u32 s17, s5, 0
	s_add_u32 s18, s6, 0x2400
	s_addc_u32 s19, s7, 0
	v_mov_b32_e32 v4, 1
	v_mov_b32_e32 v5, 0
	global_atomic_add v3, v5, v4, s[2:3] sc0
	s_waitcnt vmcnt(0) lgkmcnt(0)
	v_readfirstlane_b32 s10, v2
	v_readfirstlane_b32 s11, v0
	v_readfirstlane_b32 s12, v3
	s_mul_i32 s10, s10, 2
	s_mul_i32 s11, s11, 2
	s_add_i32 s12, s12, 1
	s_cmp_lg_u32 s12, s10
	s_cbranch_scc1 .Lxb2_poll
	buffer_wbl2 sc1
	s_waitcnt vmcnt(0)
	global_atomic_add v3, v5, v4, s[16:17] sc0
	s_waitcnt vmcnt(0)
	v_readfirstlane_b32 s12, v3
	s_add_i32 s12, s12, 1
	s_cmp_lg_u32 s12, s11
	s_cbranch_scc1 .Lxb2_poll
	global_atomic_add v5, v4, s[18:19]
	global_atomic_add v5, v4, s[18:19] offset:256
	global_atomic_add v5, v4, s[18:19] offset:512
	global_atomic_add v5, v4, s[18:19] offset:768
	global_atomic_add v5, v4, s[18:19] offset:1024
	global_atomic_add v5, v4, s[18:19] offset:1280
	global_atomic_add v5, v4, s[18:19] offset:1536
	global_atomic_add v5, v4, s[18:19] offset:1792
	global_atomic_add v5, v4, s[18:19] offset:2048
	global_atomic_add v5, v4, s[18:19] offset:2304
	global_atomic_add v5, v4, s[18:19] offset:2560
	global_atomic_add v5, v4, s[18:19] offset:2816
	global_atomic_add v5, v4, s[18:19] offset:3072
	global_atomic_add v5, v4, s[18:19] offset:3328
	global_atomic_add v5, v4, s[18:19] offset:3584
	global_atomic_add v5, v4, s[18:19] offset:3840
	buffer_inv sc1
	s_waitcnt vmcnt(0)
	s_branch .Lxb2_out

.LBB0_2292:
	v_readlane_b32 s2, v254, 8
	v_readlane_b32 s6, v254, 6
	v_readlane_b32 s7, v254, 7
	v_readlane_b32 s4, v254, 4
	v_readlane_b32 s5, v254, 5
	s_lshl_b32 s2, s2, 8
	s_add_u32 s2, s6, s2
	s_addc_u32 s3, s7, 0
	s_add_u32 s8, s2, 0x2400
	s_addc_u32 s9, s3, 0
	s_add_u32 s2, s2, 0x1400
	s_addc_u32 s3, s3, 0
	s_add_u32 s14, s4, 0x4200
	s_addc_u32 s15, s5, 0
	s_add_u32 s16, s4, 0x7400
	s_addc_u32 s17, s5, 0
	s_add_u32 s18, s6, 0x2400
	s_addc_u32 s19, s7, 0
	v_mov_b32_e32 v4, 1
	v_mov_b32_e32 v5, 0
	global_atomic_add v3, v5, v4, s[2:3] sc0
	s_waitcnt vmcnt(0) lgkmcnt(0)
	v_readfirstlane_b32 s10, v2
	v_readfirstlane_b32 s11, v0
	v_readfirstlane_b32 s12, v3
	s_mul_i32 s10, s10, 3
	s_mul_i32 s11, s11, 3
	s_add_i32 s12, s12, 1
	s_cmp_lg_u32 s12, s10
	s_cbranch_scc1 .Lxb3_poll
	buffer_wbl2 sc1
	s_waitcnt vmcnt(0)
	global_atomic_add v3, v5, v4, s[16:17] sc0
	s_waitcnt vmcnt(0)
	v_readfirstlane_b32 s12, v3
	s_add_i32 s12, s12, 1
	s_cmp_lg_u32 s12, s11
	s_cbranch_scc1 .Lxb3_poll
	global_atomic_add v5, v4, s[18:19]
	global_atomic_add v5, v4, s[18:19] offset:256
	global_atomic_add v5, v4, s[18:19] offset:512
	global_atomic_add v5, v4, s[18:19] offset:768
	global_atomic_add v5, v4, s[18:19] offset:1024
	global_atomic_add v5, v4, s[18:19] offset:1280
	global_atomic_add v5, v4, s[18:19] offset:1536
	global_atomic_add v5, v4, s[18:19] offset:1792
	global_atomic_add v5, v4, s[18:19] offset:2048
	global_atomic_add v5, v4, s[18:19] offset:2304
	global_atomic_add v5, v4, s[18:19] offset:2560
	global_atomic_add v5, v4, s[18:19] offset:2816
	global_atomic_add v5, v4, s[18:19] offset:3072
	global_atomic_add v5, v4, s[18:19] offset:3328
	global_atomic_add v5, v4, s[18:19] offset:3584
	global_atomic_add v5, v4, s[18:19] offset:3840
	buffer_inv sc1
	s_waitcnt vmcnt(0)
	s_branch .Lxb3_out

.LBB0_3527:
	v_readlane_b32 s2, v254, 8
	v_readlane_b32 s6, v254, 6
	v_readlane_b32 s7, v254, 7
	v_readlane_b32 s4, v254, 4
	v_readlane_b32 s5, v254, 5
	s_lshl_b32 s2, s2, 8
	s_add_u32 s2, s6, s2
	s_addc_u32 s3, s7, 0
	s_add_u32 s8, s2, 0x2400
	s_addc_u32 s9, s3, 0
	s_add_u32 s2, s2, 0x1400
	s_addc_u32 s3, s3, 0
	s_add_u32 s14, s4, 0x4200
	s_addc_u32 s15, s5, 0
	s_add_u32 s16, s4, 0x7400
	s_addc_u32 s17, s5, 0
	s_add_u32 s18, s6, 0x2400
	s_addc_u32 s19, s7, 0
	v_mov_b32_e32 v4, 1
	v_mov_b32_e32 v5, 0
	global_atomic_add v3, v5, v4, s[2:3] sc0
	s_waitcnt vmcnt(0) lgkmcnt(0)
	v_readfirstlane_b32 s10, v2
	v_readfirstlane_b32 s11, v0
	v_readfirstlane_b32 s12, v3
	s_mul_i32 s10, s10, 4
	s_mul_i32 s11, s11, 4
	s_add_i32 s12, s12, 1
	s_cmp_lg_u32 s12, s10
	s_cbranch_scc1 .Lxb4_poll
	buffer_wbl2 sc1
	s_waitcnt vmcnt(0)
	global_atomic_add v3, v5, v4, s[16:17] sc0
	s_waitcnt vmcnt(0)
	v_readfirstlane_b32 s12, v3
	s_add_i32 s12, s12, 1
	s_cmp_lg_u32 s12, s11
	s_cbranch_scc1 .Lxb4_poll
	global_atomic_add v5, v4, s[18:19]
	global_atomic_add v5, v4, s[18:19] offset:256
	global_atomic_add v5, v4, s[18:19] offset:512
	global_atomic_add v5, v4, s[18:19] offset:768
	global_atomic_add v5, v4, s[18:19] offset:1024
	global_atomic_add v5, v4, s[18:19] offset:1280
	global_atomic_add v5, v4, s[18:19] offset:1536
	global_atomic_add v5, v4, s[18:19] offset:1792
	global_atomic_add v5, v4, s[18:19] offset:2048
	global_atomic_add v5, v4, s[18:19] offset:2304
	global_atomic_add v5, v4, s[18:19] offset:2560
	global_atomic_add v5, v4, s[18:19] offset:2816
	global_atomic_add v5, v4, s[18:19] offset:3072
	global_atomic_add v5, v4, s[18:19] offset:3328
	global_atomic_add v5, v4, s[18:19] offset:3584
	global_atomic_add v5, v4, s[18:19] offset:3840
	buffer_inv sc1
	s_waitcnt vmcnt(0)
	s_branch .Lxb4_out
